# baseline (speedup 1.0000x reference)
; __device__ __forceinline__ int sub_op() { return __builtin_amdgcn_readfirstlane((int)(threadIdx.x >> 8)); }
; #define LAS __attribute__((address_space(3)))
; __global__ void __launch_bounds__(512, 2) mega_kernel(Params p) {
;   __shared__ __attribute__((aligned(16))) char smem[2 * SMEM_BYTES + 16];
;   __shared__ uint4 xb_words;
;   if (threadIdx.x == 0) xb_words = make_uint4(0u, 0u, 0u, 0u);
;   __syncthreads();
;   const XcdBarrier xb = xcd_barrier_post(p.bar, (volatile LAS unsigned*)&xb_words, (unsigned)(p.nblk >> 1));
;   run_range<0, NPHASE>(p, smem + sub_op() * SMEM_BYTES, smem, xb);
_Z11mega_kernel6Params:
	s_load_dwordx4 s[4:7], s[0:1], 0x140
	v_readfirstlane_b32 vcc_lo, v0
	s_bfe_u32 vcc_lo, vcc_lo, 0x20008
	s_cmp_eq_u32 vcc_lo, 0
	s_cbranch_scc0 .Lprio_skip
	s_setprio 1
